# SSD output part: skip-connection x values read from LDS before the block's MFMAs instead of one round trip per element
# speedup vs baseline: 1.0026x; 1.0026x over previous
.LBB0_35:
	s_mov_b32 s44, 0
	s_add_i32 s2, s44, s76
	s_waitcnt vmcnt(0)
	v_mbcnt_lo_u32_b32 v0, -1, 0
	v_mbcnt_hi_u32_b32 v0, -1, v0
	s_add_i32 s18, s44, s69
	v_lshl_add_u32 v176, s2, 6, v0
	s_add_i32 s82, s44, s72
	v_readfirstlane_b32 s2, v176
	s_ashr_i32 s6, s2, 6
	v_readlane_b32 s4, v254, 11
	s_cmp_gt_u32 s4, 16
	s_cselect_b64 s[2:3], -1, 0
	s_cmp_lt_u32 s4, 17
	s_cselect_b64 s[10:11], -1, 0
	s_and_b64 s[4:5], s[10:11], exec
	s_mov_b32 s4, 0x12000
	s_cselect_b32 s4, s4, 0x10000
	s_lshl_b32 s5, s82, 3
	s_abs_i32 s7, s5
	v_cvt_f32_u32_e32 v1, s7
	s_mov_b32 s14, s18
	v_writelane_b32 v254, s14, 41
	s_lshl_b32 s13, s18, 3
	v_rcp_iflag_f32_e32 v1, v1
	v_writelane_b32 v254, s15, 42
	s_add_i32 s6, s6, s13
	s_sub_i32 s13, 0, s7
	v_mul_f32_e32 v1, 0x4f7ffffe, v1
	v_cvt_u32_f32_e32 v1, v1
	s_add_i32 s12, s4, s5
	s_add_i32 s12, s12, -1
	s_xor_b32 s5, s12, s5
	v_readfirstlane_b32 s14, v1
	s_mul_i32 s13, s13, s14
	s_mul_hi_u32 s13, s14, s13
	s_abs_i32 s12, s12
	s_add_i32 s14, s14, s13
	s_mul_hi_u32 s13, s12, s14
	s_mul_i32 s14, s13, s7
	s_sub_i32 s12, s12, s14
	s_ashr_i32 s5, s5, 31
	s_add_i32 s14, s13, 1
	s_sub_i32 s15, s12, s7
	s_cmp_ge_u32 s12, s7
	s_cselect_b32 s13, s14, s13
	s_cselect_b32 s12, s15, s12
	s_add_i32 s14, s13, 1
	s_cmp_ge_u32 s12, s7
	s_cselect_b32 s7, s14, s13
	s_xor_b32 s7, s7, s5
	s_sub_i32 s5, s7, s5
	s_mul_i32 s56, s5, s6
	s_add_i32 s5, s56, s5
	s_min_i32 s57, s5, s4
	s_cmp_ge_i32 s56, s57
	s_mov_b32 s54, 0x800000
	s_cbranch_scc1 .LBB0_134
	v_readlane_b32 s28, v254, 11
	s_cmp_lg_u32 s28, 21
	s_cselect_b64 s[6:7], -1, 0
	s_cmp_eq_u32 s28, 21
	s_cselect_b64 s[12:13], -1, 0
	s_cmp_eq_u32 s28, 17
	s_cselect_b64 s[14:15], -1, 0
	s_lshl_b64 s[4:5], s[44:45], 3
	s_add_u32 s22, s70, s4
	v_readlane_b32 s24, v253, 62
	s_addc_u32 s23, s71, s5
	v_readlane_b32 s26, v254, 0
	v_readlane_b32 s27, v254, 1
	s_add_u32 s4, s26, s44
	s_addc_u32 s5, s27, 0
	s_lshl_b64 s[18:19], s[44:45], 2
	v_readlane_b32 s25, v253, 63
	s_add_u32 s58, s24, s18
	s_addc_u32 s59, s25, s19
	s_cmp_eq_u32 s28, 10
	s_cselect_b64 s[18:19], -1, 0
	s_and_b64 s[20:21], s[18:19], exec
	s_movk_i32 s20, 0x400
	s_cselect_b32 s60, s20, 0x1000
	s_cselect_b32 s61, 0, 0xc00
	s_or_b64 s[12:13], s[18:19], s[12:13]
	s_and_b64 s[18:19], s[12:13], exec
	s_cselect_b32 s18, 64, 48
	s_add_u32 s18, s22, s18
	s_addc_u32 s19, s23, 0
	s_load_dwordx2 s[18:19], s[18:19], 0x0
	s_and_b64 s[10:11], s[10:11], exec
	s_cselect_b32 s20, 0, 0x1000
	v_and_b32_e32 v34, 63, v0
	v_lshlrev_b32_e32 v192, 5, v34
	s_waitcnt lgkmcnt(0)
	s_add_u32 s10, s18, s20
	s_addc_u32 s11, s19, 0
	s_and_b64 s[12:13], s[12:13], exec
	s_cselect_b32 s12, 0x48, 56
	s_add_u32 s12, s22, s12
	s_addc_u32 s13, s23, 0
	s_load_dwordx2 s[12:13], s[12:13], 0x0
	v_xor_b32_e32 v32, 1, v229
	v_cmp_lt_i32_e32 vcc, v32, v231
	v_mov_b32_e32 v33, v193
	v_mov_b32_e32 v62, 0
	s_waitcnt lgkmcnt(0)
	s_add_u32 s12, s12, s20
	s_addc_u32 s13, s13, 0
	global_load_dwordx4 v[0:3], v192, s[10:11] offset:16
	global_load_dwordx4 v[4:7], v192, s[10:11]
	global_load_dwordx4 v[8:11], v192, s[12:13] offset:16
	global_load_dwordx4 v[12:15], v192, s[12:13]
	global_load_dwordx4 v[16:19], v192, s[10:11] offset:2064
	global_load_dwordx4 v[20:23], v192, s[10:11] offset:2048
	global_load_dwordx4 v[24:27], v192, s[12:13] offset:2064
	global_load_dwordx4 v[28:31], v192, s[12:13] offset:2048
	v_cndmask_b32_e32 v32, v229, v32, vcc
	v_lshlrev_b32_e32 v109, 2, v32
	v_xor_b32_e32 v32, 2, v229
	v_cmp_lt_i32_e32 vcc, v32, v231
	s_cmp_eq_u32 s28, 6
	s_cselect_b64 s[10:11], -1, 0
	v_cndmask_b32_e32 v32, v229, v32, vcc
	v_lshlrev_b32_e32 v121, 2, v32
	v_xor_b32_e32 v32, 4, v229
	v_cmp_lt_i32_e32 vcc, v32, v231
	s_and_b64 s[12:13], s[10:11], exec
	s_mov_b32 s12, 0x44d4000
	v_cndmask_b32_e32 v32, v229, v32, vcc
	v_lshlrev_b32_e32 v122, 2, v32
	v_xor_b32_e32 v32, 8, v229
	v_cmp_lt_i32_e32 vcc, v32, v231
	s_cselect_b32 s12, s12, 0x459a000
	s_or_b64 s[10:11], s[10:11], s[14:15]
	v_cndmask_b32_e32 v32, v229, v32, vcc
	v_lshlrev_b32_e32 v123, 2, v32
	v_xor_b32_e32 v32, 16, v229
	v_cmp_lt_i32_e32 vcc, v32, v231
	s_add_u32 s62, s4, 0x38260000
	s_addc_u32 s63, s5, 0
	v_cndmask_b32_e32 v32, v229, v32, vcc
	v_lshlrev_b32_e32 v124, 2, v32
	v_xor_b32_e32 v32, 32, v229
	s_add_u32 s64, s4, 0x3d2e4000
	v_cmp_lt_i32_e32 vcc, v32, v231
	s_addc_u32 s65, s5, 0
	s_add_u32 s14, s4, s12
	v_cndmask_b32_e32 v32, v229, v32, vcc
	v_lshlrev_b32_e32 v125, 2, v32
	v_lshlrev_b32_e32 v32, 4, v34
	s_addc_u32 s15, s5, 0
	v_lshl_add_u64 v[32:33], s[4:5], 0, v[32:33]
	s_mov_b64 s[4:5], 0x4660000
	v_lshl_add_u64 v[110:111], v[32:33], 0, s[4:5]
	v_cmp_eq_u32_e32 vcc, 0, v34
	s_mov_b64 s[4:5], 0x16660000
	v_lshlrev_b32_e32 v108, 3, v34
	s_mov_b32 s68, -1
	s_and_b64 s[12:13], s[6:7], vcc
	v_lshl_add_u64 v[112:113], s[14:15], 0, v[192:193]
	v_lshl_add_u64 v[114:115], v[32:33], 0, s[4:5]
	v_mov_b32_e32 v63, v62
	v_mov_b32_e32 v54, v62
	v_mov_b32_e32 v55, v62
	v_mov_b32_e32 v60, v62
	v_mov_b32_e32 v61, v62
	v_mov_b32_e32 v52, v62
	v_mov_b32_e32 v53, v62
	v_mov_b32_e32 v58, v62
	v_mov_b32_e32 v59, v62
	v_mov_b32_e32 v50, v62
	v_mov_b32_e32 v51, v62
	v_mov_b32_e32 v56, v62
	v_mov_b32_e32 v57, v62
	v_mov_b32_e32 v48, v62
	v_mov_b32_e32 v49, v62
	v_mov_b32_e32 v38, v62
	v_mov_b32_e32 v39, v62
	v_mov_b32_e32 v46, v62
	v_mov_b32_e32 v47, v62
	v_mov_b32_e32 v36, v62
	v_mov_b32_e32 v37, v62
	v_mov_b32_e32 v44, v62
	v_mov_b32_e32 v45, v62
	v_mov_b32_e32 v34, v62
	v_mov_b32_e32 v35, v62
	v_mov_b32_e32 v42, v62
	v_mov_b32_e32 v43, v62
	v_mov_b32_e32 v32, v62
	v_mov_b32_e32 v33, v62
	v_mov_b32_e32 v40, v62
	v_mov_b32_e32 v41, v62
	s_branch .LBB0_38
	s_nop 0
	s_nop 0
	s_nop 0
	s_nop 0
	s_nop 0
	s_nop 0
	s_nop 0
	s_nop 0
	s_nop 0
	s_nop 0
	s_nop 0
	s_nop 0
	s_nop 0
	s_nop 0
	s_nop 0
	s_nop 0

.LBB0_289:
	s_waitcnt lgkmcnt(4)
	v_mul_f32_e32 v80, 0x3fb8aa3b, v80
	v_exp_f32_e32 v89, v80
	v_add_u32_e32 v80, s17, v108
	s_waitcnt lgkmcnt(0)
	s_barrier
	ds_write_b64 v160, v[66:67] offset:32768
	ds_write_b64 v161, v[64:65] offset:32768
	ds_write_b64 v162, v[70:71] offset:32768
	ds_write_b64 v163, v[68:69] offset:32768
	ds_write_b64 v164, v[74:75] offset:32768
	ds_write_b64 v165, v[72:73] offset:32768
	ds_write_b64 v166, v[76:77] offset:32768
	ds_write_b64 v167, v[78:79] offset:32768
	s_waitcnt lgkmcnt(0)
	s_barrier
	ds_read_b128 v[76:79], v186 offset:32768
	ds_read_b128 v[72:75], v187 offset:32768
	ds_read_b128 v[68:71], v188 offset:32768
	ds_read_b128 v[64:67], v189 offset:32768
	ds_read_u16 v236, v168
	ds_read_u16 v237, v169
	ds_read_u16 v242, v170
	ds_read_u16 v243, v171
	ds_read_b128 v[216:219], v80
	v_add_u32_e32 v90, s66, v108
	ds_read_b128 v[220:223], v90
	v_add_u32_e32 v90, s17, v109
	ds_read_b128 v[232:235], v90
	v_add_u32_e32 v90, s66, v109
	ds_read_b128 v[246:249], v90
	v_add_u32_e32 v90, s17, v110
	ds_read_b128 v[202:205], v90
	v_add_u32_e32 v90, s66, v110
	ds_read_b128 v[206:209], v90
	s_andn2_b64 vcc, exec, s[30:31]
	s_waitcnt lgkmcnt(5)
	v_mfma_f32_16x16x32_bf16 v[80:83], v[216:219], v[76:79], 0
	v_add_u32_e32 v90, s17, v111
	ds_read_b128 v[216:219], v90
	s_waitcnt lgkmcnt(5)
	v_mfma_f32_16x16x32_bf16 v[84:87], v[220:223], v[60:63], 0
	v_add_u32_e32 v90, s66, v111
	ds_read_b128 v[220:223], v90
	s_waitcnt lgkmcnt(5)
	v_mfma_f32_16x16x32_bf16 v[80:83], v[232:235], v[72:75], v[80:83]
	s_waitcnt lgkmcnt(4)
	v_mfma_f32_16x16x32_bf16 v[84:87], v[246:249], v[56:59], v[84:87]
	s_waitcnt lgkmcnt(3)
	v_mfma_f32_16x16x32_bf16 v[80:83], v[202:205], v[68:71], v[80:83]
	s_waitcnt lgkmcnt(2)
	v_mfma_f32_16x16x32_bf16 v[84:87], v[206:209], v[52:55], v[84:87]
	s_waitcnt lgkmcnt(1)
	v_mfma_f32_16x16x32_bf16 v[80:83], v[216:219], v[64:67], v[80:83]
	s_waitcnt lgkmcnt(0)
	v_mfma_f32_16x16x32_bf16 v[84:87], v[220:223], v[48:51], v[84:87]
	s_nop 7
	v_fma_f32 v80, v89, v84, v80
	v_cndmask_b32_e64 v84, 0, 1, s[30:31]
	v_cmp_ne_u32_e64 s[34:35], 1, v84
	s_cbranch_vccnz .LBB0_297
	v_lshlrev_b32_e32 v84, 16, v236
	s_waitcnt vmcnt(0)
	v_fmac_f32_e32 v80, v200, v84
	s_and_b64 vcc, exec, s[34:35]
	v_fma_f32 v81, v89, v85, v81
	s_cbranch_vccz .LBB0_298

.LBB0_292:
	v_lshlrev_b32_e32 v84, 16, v242
	s_waitcnt vmcnt(0)
	v_fmac_f32_e32 v82, v200, v84
	s_and_b64 vcc, exec, s[34:35]
	v_fmac_f32_e32 v83, v89, v87
	s_cbranch_vccz .LBB0_300
	s_branch .LBB0_301

.LBB0_298:
	v_lshlrev_b32_e32 v84, 16, v237
	s_waitcnt vmcnt(0)
	v_fmac_f32_e32 v81, v200, v84
	s_and_b64 vcc, exec, s[34:35]
	v_fma_f32 v82, v89, v86, v82
	s_cbranch_vccz .LBB0_292

.LBB0_300:
	v_lshlrev_b32_e32 v84, 16, v243
	s_waitcnt vmcnt(0)
	v_fmac_f32_e32 v83, v200, v84
.LBB0_301:
	s_add_i32 s44, s44, -2
	s_lshl_b64 s[36:37], s[44:45], 17
	v_lshl_add_u64 v[100:101], v[92:93], 0, s[36:37]
	v_cvt_pk_bf16_f32 v80, v80, v81
	v_cvt_pk_bf16_f32 v81, v82, v83
	global_store_dwordx2 v[100:101], v[80:81], off
	v_add_u32_e32 v80, s17, v114
	ds_read_u16 v236, v198 offset:4096
	ds_read_u16 v237, v172
	ds_read_u16 v242, v173
	ds_read_u16 v243, v174
	ds_read_b128 v[216:219], v80
	v_add_u32_e32 v90, s66, v114
	ds_read_b128 v[220:223], v90
	v_add_u32_e32 v90, s17, v115
	ds_read_b128 v[232:235], v90
	v_add_u32_e32 v90, s66, v115
	ds_read_b128 v[246:249], v90
	v_add_u32_e32 v90, s17, v116
	ds_read_b128 v[202:205], v90
	v_add_u32_e32 v90, s66, v116
	ds_read_b128 v[206:209], v90
	s_and_b64 vcc, exec, s[34:35]
	s_waitcnt lgkmcnt(5)
	v_mfma_f32_16x16x32_bf16 v[80:83], v[216:219], v[76:79], 0
	v_add_u32_e32 v90, s17, v117
	ds_read_b128 v[216:219], v90
	s_waitcnt lgkmcnt(5)
	v_mfma_f32_16x16x32_bf16 v[84:87], v[220:223], v[60:63], 0
	v_add_u32_e32 v90, s66, v117
	ds_read_b128 v[220:223], v90
	s_waitcnt lgkmcnt(5)
	v_mfma_f32_16x16x32_bf16 v[80:83], v[232:235], v[72:75], v[80:83]
	s_waitcnt lgkmcnt(4)
	v_mfma_f32_16x16x32_bf16 v[84:87], v[246:249], v[56:59], v[84:87]
	s_waitcnt lgkmcnt(3)
	v_mfma_f32_16x16x32_bf16 v[80:83], v[202:205], v[68:71], v[80:83]
	s_waitcnt lgkmcnt(2)
	v_mfma_f32_16x16x32_bf16 v[84:87], v[206:209], v[52:55], v[84:87]
	s_waitcnt lgkmcnt(1)
	v_mfma_f32_16x16x32_bf16 v[80:83], v[216:219], v[64:67], v[80:83]
	s_waitcnt lgkmcnt(0)
	v_mfma_f32_16x16x32_bf16 v[84:87], v[220:223], v[48:51], v[84:87]
	s_nop 7
	v_fma_f32 v80, v89, v84, v80
	s_cbranch_vccnz .LBB0_305
	v_lshlrev_b32_e32 v84, 16, v236
	s_waitcnt vmcnt(1)
	v_fmac_f32_e32 v80, v200, v84
	s_and_b64 vcc, exec, s[34:35]
	v_fma_f32 v81, v89, v85, v81
	s_cbranch_vccz .LBB0_306

.LBB0_304:
	v_lshlrev_b32_e32 v84, 16, v242
	s_waitcnt vmcnt(1)
	v_fmac_f32_e32 v82, v200, v84
	s_and_b64 vcc, exec, s[34:35]
	v_fmac_f32_e32 v83, v89, v87
	s_cbranch_vccz .LBB0_308
	s_branch .LBB0_309

.LBB0_306:
	v_lshlrev_b32_e32 v84, 16, v237
	s_waitcnt vmcnt(1)
	v_fmac_f32_e32 v81, v200, v84
	s_and_b64 vcc, exec, s[34:35]
	v_fma_f32 v82, v89, v86, v82
	s_cbranch_vccz .LBB0_304

.LBB0_308:
	v_lshlrev_b32_e32 v84, 16, v243
	s_waitcnt vmcnt(1)
	v_fmac_f32_e32 v83, v200, v84
.LBB0_309:
	v_cvt_pk_bf16_f32 v80, v80, v81
	v_cvt_pk_bf16_f32 v81, v82, v83
	global_store_dwordx2 v[100:101], v[80:81], off offset:32
	v_add_u32_e32 v80, s17, v120
	ds_read_u16 v236, v198 offset:8192
	ds_read_u16 v237, v175
	ds_read_u16 v242, v177
	ds_read_u16 v243, v178
	ds_read_b128 v[216:219], v80
	v_add_u32_e32 v90, s66, v120
	ds_read_b128 v[220:223], v90
	v_add_u32_e32 v90, s17, v121
	ds_read_b128 v[232:235], v90
	v_add_u32_e32 v90, s66, v121
	ds_read_b128 v[246:249], v90
	v_add_u32_e32 v90, s17, v122
	ds_read_b128 v[202:205], v90
	v_add_u32_e32 v90, s66, v122
	ds_read_b128 v[206:209], v90
	s_and_b64 vcc, exec, s[34:35]
	s_waitcnt lgkmcnt(5)
	v_mfma_f32_16x16x32_bf16 v[80:83], v[216:219], v[76:79], 0
	v_add_u32_e32 v90, s17, v123
	ds_read_b128 v[216:219], v90
	s_waitcnt lgkmcnt(5)
	v_mfma_f32_16x16x32_bf16 v[84:87], v[220:223], v[60:63], 0
	v_add_u32_e32 v90, s66, v123
	ds_read_b128 v[220:223], v90
	s_waitcnt lgkmcnt(5)
	v_mfma_f32_16x16x32_bf16 v[80:83], v[232:235], v[72:75], v[80:83]
	s_waitcnt lgkmcnt(4)
	v_mfma_f32_16x16x32_bf16 v[84:87], v[246:249], v[56:59], v[84:87]
	s_waitcnt lgkmcnt(3)
	v_mfma_f32_16x16x32_bf16 v[80:83], v[202:205], v[68:71], v[80:83]
	s_waitcnt lgkmcnt(2)
	v_mfma_f32_16x16x32_bf16 v[84:87], v[206:209], v[52:55], v[84:87]
	s_waitcnt lgkmcnt(1)
	v_mfma_f32_16x16x32_bf16 v[80:83], v[216:219], v[64:67], v[80:83]
	s_waitcnt lgkmcnt(0)
	v_mfma_f32_16x16x32_bf16 v[84:87], v[220:223], v[48:51], v[84:87]
	s_nop 7
	v_fma_f32 v80, v89, v84, v80
	s_cbranch_vccnz .LBB0_313
	v_lshlrev_b32_e32 v84, 16, v236
	s_waitcnt vmcnt(2)
	v_fmac_f32_e32 v80, v200, v84
	s_and_b64 vcc, exec, s[34:35]
	v_fma_f32 v81, v89, v85, v81
	s_cbranch_vccz .LBB0_314

.LBB0_312:
	v_lshlrev_b32_e32 v84, 16, v242
	s_waitcnt vmcnt(2)
	v_fmac_f32_e32 v82, v200, v84
	s_and_b64 vcc, exec, s[34:35]
	v_fmac_f32_e32 v83, v89, v87
	s_cbranch_vccz .LBB0_316
	s_branch .LBB0_317

.LBB0_314:
	v_lshlrev_b32_e32 v84, 16, v237
	s_waitcnt vmcnt(2)
	v_fmac_f32_e32 v81, v200, v84
	s_and_b64 vcc, exec, s[34:35]
	v_fma_f32 v82, v89, v86, v82
	s_cbranch_vccz .LBB0_312

.LBB0_316:
	v_lshlrev_b32_e32 v84, 16, v243
	s_waitcnt vmcnt(2)
	v_fmac_f32_e32 v83, v200, v84
.LBB0_317:
	v_cvt_pk_bf16_f32 v80, v80, v81
	v_cvt_pk_bf16_f32 v81, v82, v83
	global_store_dwordx2 v[100:101], v[80:81], off offset:64
	v_add_u32_e32 v80, s17, v126
	ds_read_u16 v236, v198 offset:12288
	ds_read_u16 v237, v179
	ds_read_u16 v242, v180
	ds_read_u16 v243, v181
	ds_read_b128 v[216:219], v80
	v_add_u32_e32 v90, s66, v126
	ds_read_b128 v[220:223], v90
	v_add_u32_e32 v90, s17, v127
	ds_read_b128 v[232:235], v90
	v_add_u32_e32 v90, s66, v127
	ds_read_b128 v[246:249], v90
	v_add_u32_e32 v90, s17, v128
	ds_read_b128 v[202:205], v90
	v_add_u32_e32 v90, s66, v128
	ds_read_b128 v[206:209], v90
	s_and_b64 vcc, exec, s[34:35]
	s_waitcnt lgkmcnt(5)
	v_mfma_f32_16x16x32_bf16 v[80:83], v[216:219], v[76:79], 0
	v_add_u32_e32 v90, s17, v129
	ds_read_b128 v[216:219], v90
	s_waitcnt lgkmcnt(5)
	v_mfma_f32_16x16x32_bf16 v[84:87], v[220:223], v[60:63], 0
	v_add_u32_e32 v90, s66, v129
	ds_read_b128 v[220:223], v90
	s_waitcnt lgkmcnt(5)
	v_mfma_f32_16x16x32_bf16 v[80:83], v[232:235], v[72:75], v[80:83]
	s_waitcnt lgkmcnt(4)
	v_mfma_f32_16x16x32_bf16 v[84:87], v[246:249], v[56:59], v[84:87]
	s_waitcnt lgkmcnt(3)
	v_mfma_f32_16x16x32_bf16 v[80:83], v[202:205], v[68:71], v[80:83]
	s_waitcnt lgkmcnt(2)
	v_mfma_f32_16x16x32_bf16 v[84:87], v[206:209], v[52:55], v[84:87]
	s_waitcnt lgkmcnt(1)
	v_mfma_f32_16x16x32_bf16 v[80:83], v[216:219], v[64:67], v[80:83]
	s_waitcnt lgkmcnt(0)
	v_mfma_f32_16x16x32_bf16 v[84:87], v[220:223], v[48:51], v[84:87]
	s_nop 7
	v_mov_b32_e32 v52, v80
	v_mov_b32_e32 v53, v81
	v_mov_b32_e32 v54, v82
	v_mov_b32_e32 v55, v83
	v_mov_b32_e32 v48, v84
	v_mov_b32_e32 v49, v85
	v_mov_b32_e32 v50, v86
	v_mov_b32_e32 v51, v87
	s_nop 7
	v_fma_f32 v48, v89, v48, v52
	s_cbranch_vccnz .LBB0_321
	v_lshlrev_b32_e32 v52, 16, v236
	s_waitcnt vmcnt(3)
	v_fmac_f32_e32 v48, v200, v52
	s_and_b64 vcc, exec, s[34:35]
	v_fma_f32 v49, v89, v49, v53
	s_cbranch_vccz .LBB0_322

.LBB0_320:
	v_lshlrev_b32_e32 v52, 16, v242
	s_waitcnt vmcnt(3)
	v_fmac_f32_e32 v50, v200, v52
	s_and_b64 vcc, exec, s[34:35]
	v_fmac_f32_e32 v55, v89, v51
	s_cbranch_vccnz .LBB0_207
	s_branch .LBB0_324

.LBB0_322:
	v_lshlrev_b32_e32 v52, 16, v237
	s_waitcnt vmcnt(3)
	v_fmac_f32_e32 v49, v200, v52
	s_and_b64 vcc, exec, s[34:35]
	v_fma_f32 v50, v89, v50, v54
	s_cbranch_vccz .LBB0_320

.LBB0_324:
	v_lshlrev_b32_e32 v51, 16, v243
	s_waitcnt vmcnt(3)
	v_fmac_f32_e32 v55, v200, v51
	s_branch .LBB0_207
